# v39 + GEMM prologue: second staging batch issued before the first wait (both batches in flight)
# baseline (speedup 1.0000x reference)
; #define PG8_STAGE(bufoff, gbase, voff) do { _Pragma("unroll") for (int _i = 0; _i < 2; ++_i) glds16_s((gbase), (voff)[_i], ldsb + (unsigned)((bufoff) + _i * 8192)); } while (0)
; #define PG8_WAIT_V(n) asm volatile("s_waitcnt vmcnt(" #n ")" ::: "memory")
; #define PG8_BAR __builtin_amdgcn_s_barrier()
; template <class Prob, class Epi, bool I8 = false, bool ALIGN_EPI = true, bool SP2 = true>
; __device__ __forceinline__ void gemm_phase(LAS unsigned char* lds, int wave, const Prob& P, const Epi& E) {
;     ...
;     const char* cA = P.a_tile(cur); const char* cB = P.b_tile(cur);
;     if constexpr (SP2) {
;         PG8_STAGE(PG8_SB(0, 0), cB, voffB); PG8_STAGE(PG8_SB(0, 1), cB + hstepB, voffB); PG8_STAGE(PG8_SA(0, 0), cA, voffA); PG8_STAGE(PG8_SA(0, 1), cA + hstepA, voffA);
;         if (wr == 1) PG8_BAR;
;         PG8_WAIT_V(2); PG8_BAR;
;         PG8_STAGE(PG8_SB(1, 0), cB + kstep, voffB); PG8_STAGE(PG8_SA(1, 0), cA + kstep, voffA); PG8_STAGE(PG8_SB(1, 1), cB + hstepB + kstep, voffB);
;         PG8_WAIT_V(6); PG8_BAR;
.LBB0_219:
	s_add_u32 s16, s44, 0x80
	s_addc_u32 s17, s45, 0
	s_add_u32 s22, s42, 0x80
	s_addc_u32 s23, s43, 0
	s_add_u32 s28, s44, 0x80080
	v_and_b32_e32 v1, 48, v0
	v_lshlrev_b32_e32 v2, 6, v0
	s_movk_i32 s5, 0x3c0
	v_lshlrev_b32_e32 v0, 2, v0
	s_addc_u32 s29, s45, 0
	s_lshl_b32 s69, s1, 6
	s_lshl_b32 s1, s1, 13
	v_and_or_b32 v1, v2, s5, v1
	v_and_b32_e32 v0, 32, v0
	v_bitop3_b32 v2, v1, s1, v0 bitop3:0xde
	s_lshl_b32 s1, s4, 5
	s_and_b32 s72, s1, 0x60
	s_lshl_b32 s1, s72, 7
	v_bitop3_b32 v0, s1, v1, v0 bitop3:0xf6
	s_add_i32 s73, s56, 0x18000
	s_mov_b32 s1, m0
	s_mov_b32 m0, s73
	s_nop 0
	global_load_lds_dwordx4 v129, s[16:17]
	s_mov_b32 m0, s1
	s_add_i32 s74, s56, 0x1a000
	s_mov_b32 s1, m0
	s_mov_b32 m0, s74
	s_nop 0
	global_load_lds_dwordx4 v131, s[16:17]
	s_mov_b32 m0, s1
	s_add_i32 s75, s56, 0x8000
	s_mov_b32 s1, m0
	s_mov_b32 m0, s75
	s_nop 0
	global_load_lds_dwordx4 v128, s[22:23]
	s_mov_b32 m0, s1
	s_add_i32 s76, s56, 0xa000
	s_mov_b32 s1, m0
	s_mov_b32 m0, s76
	s_nop 0
	global_load_lds_dwordx4 v130, s[22:23]
	s_mov_b32 m0, s1
	s_add_i32 s77, s56, 0x1c000
	s_mov_b32 s1, m0
	s_mov_b32 m0, s77
	s_nop 0
	global_load_lds_dwordx4 v129, s[28:29]
	s_mov_b32 m0, s1
	s_add_i32 s79, s56, 0x1e000
	s_mov_b32 s1, m0
	s_mov_b32 m0, s79
	s_nop 0
	global_load_lds_dwordx4 v131, s[28:29]
	s_mov_b32 m0, s1
	s_waitcnt vmcnt(8)
	s_barrier
	s_waitcnt vmcnt(6)
	s_add_i32 s80, s56, 0xc000
	s_cmpk_lt_u32 s0, 0x100
	v_add_u32_e32 v0, 0, v0
	v_readlane_b32 s0, v254, 49
	s_cselect_b64 s[16:17], -1, 0
	s_add_i32 s81, s56, 0xe000
	s_mov_b32 s82, 0
	v_add_u32_e32 v132, 0x10000, v0
	v_add_u32_e32 v133, 0x14000, v0
	v_add_u32_e32 v134, 0, v2
	v_add_u32_e32 v135, 0x18000, v0
	v_add_u32_e32 v136, 0x1c000, v0
	v_readlane_b32 s85, v254, 47
	s_mov_b32 s86, s0
	v_readlane_b32 s84, v254, 45
	s_barrier
	v_readlane_b32 s1, v254, 50
	s_branch .LBB0_222

; #define PG8_STAGE(bufoff, gbase, voff) do { _Pragma("unroll") for (int _i = 0; _i < 2; ++_i) glds16_s((gbase), (voff)[_i], ldsb + (unsigned)((bufoff) + _i * 8192)); } while (0)
; #define PG8_WAIT_V(n) asm volatile("s_waitcnt vmcnt(" #n ")" ::: "memory")
; #define PG8_BAR __builtin_amdgcn_s_barrier()
; template <class Prob, class Epi, bool I8 = false, bool ALIGN_EPI = true, bool SP2 = true>
; __device__ __forceinline__ void gemm_phase(LAS unsigned char* lds, int wave, const Prob& P, const Epi& E) {
;     ...
;     Acc acc;
; #pragma unroll
;     for (int a = 0; a < 2; ++a)
; #pragma unroll
;         for (int b = 0; b < 2; ++b)
; #pragma unroll
;             for (int m = 0; m < 4; ++m)
; #pragma unroll
;                 for (int n = 0; n < 2; ++n) acc[a][b][m][n] = (f32x4){0.f, 0.f, 0.f, 0.f};
;     h16x8 At[4][2], B0[2][2], B1[2][2];
;     const char* cA = P.a_tile(cur); const char* cB = P.b_tile(cur);
;     if constexpr (SP2) {
;         PG8_STAGE(PG8_SB(0, 0), cB, voffB); PG8_STAGE(PG8_SB(0, 1), cB + hstepB, voffB); PG8_STAGE(PG8_SA(0, 0), cA, voffA); PG8_STAGE(PG8_SA(0, 1), cA + hstepA, voffA);
;         if (wr == 1) PG8_BAR;
;         PG8_WAIT_V(2); PG8_BAR;
;         PG8_STAGE(PG8_SB(1, 0), cB + kstep, voffB); PG8_STAGE(PG8_SA(1, 0), cA + kstep, voffA); PG8_STAGE(PG8_SB(1, 1), cB + hstepB + kstep, voffB);
;         PG8_WAIT_V(6); PG8_BAR;
.LBB0_289:
	v_and_b32_e32 v1, 48, v0
	v_lshlrev_b32_e32 v2, 6, v0
	s_movk_i32 s5, 0x3c0
	v_lshlrev_b32_e32 v0, 2, v0
	s_lshl_b32 s79, s1, 6
	s_lshl_b32 s1, s1, 13
	v_and_or_b32 v1, v2, s5, v1
	v_and_b32_e32 v0, 32, v0
	v_bitop3_b32 v2, v1, s1, v0 bitop3:0xde
	s_lshl_b32 s1, s4, 5
	s_and_b32 s64, s1, 0x60
	s_lshl_b32 s1, s64, 7
	s_add_u32 s4, s38, 0x80
	v_bitop3_b32 v1, s1, v1, v0 bitop3:0xf6
	s_addc_u32 s5, s39, 0
	s_add_i32 s80, s2, 0x18000
	s_mov_b32 s1, m0
	s_mov_b32 m0, s80
	s_nop 0
	global_load_lds_dwordx4 v136, s[4:5]
	s_mov_b32 m0, s1
	s_add_i32 s81, s2, 0x1a000
	s_mov_b32 s1, m0
	s_mov_b32 m0, s81
	s_nop 0
	global_load_lds_dwordx4 v138, s[4:5]
	s_mov_b32 m0, s1
	s_add_u32 s4, s14, 0x80
	s_addc_u32 s5, s15, 0
	s_add_i32 s82, s2, 0x8000
	s_mov_b32 s1, m0
	s_mov_b32 m0, s82
	s_nop 0
	global_load_lds_dwordx4 v148, s[4:5]
	s_mov_b32 m0, s1
	s_add_i32 s83, s2, 0xa000
	s_mov_b32 s1, m0
	s_mov_b32 m0, s83
	s_nop 0
	global_load_lds_dwordx4 v137, s[4:5]
	s_mov_b32 m0, s1
	s_add_u32 s4, s38, 0x104080
	s_addc_u32 s5, s39, 0
	s_add_i32 s84, s2, 0x1c000
	s_mov_b32 s1, m0
	s_mov_b32 m0, s84
	s_nop 0
	global_load_lds_dwordx4 v136, s[4:5]
	s_mov_b32 m0, s1
	s_add_i32 s85, s2, 0x1e000
	s_mov_b32 s1, m0
	s_mov_b32 m0, s85
	s_nop 0
	global_load_lds_dwordx4 v138, s[4:5]
	s_mov_b32 m0, s1
	s_waitcnt vmcnt(8)
	s_barrier
	s_waitcnt vmcnt(6)
	s_add_i32 s86, s2, 0xc000
	s_cmpk_lt_u32 s0, 0x100
	v_mov_b32_e32 v0, 0
	s_cselect_b64 s[28:29], -1, 0
	s_add_i32 s87, s2, 0xe000
	s_mov_b32 s75, 0
	s_mov_b32 s90, 1
	v_add_u32_e32 v139, 0, v1
	v_add_u32_e32 v149, 0, v2
	v_readlane_b32 s72, v254, 58
	v_readlane_b32 s73, v254, 57
	v_readlane_b32 s74, v252, 29
	s_mov_b32 s88, 0
	v_mov_b32_e32 v1, v0
	v_mov_b32_e32 v2, v0
	v_mov_b32_e32 v3, v0
	v_mov_b32_e32 v4, v0
	v_mov_b32_e32 v5, v0
	v_mov_b32_e32 v6, v0
	v_mov_b32_e32 v7, v0
	v_mov_b32_e32 v8, v0
	v_mov_b32_e32 v9, v0
	v_mov_b32_e32 v10, v0
	v_mov_b32_e32 v11, v0
	v_mov_b32_e32 v12, v0
	v_mov_b32_e32 v13, v0
	v_mov_b32_e32 v14, v0
	v_mov_b32_e32 v15, v0
	v_mov_b32_e32 v16, v0
	v_mov_b32_e32 v17, v0
	v_mov_b32_e32 v18, v0
	v_mov_b32_e32 v19, v0
	v_mov_b32_e32 v20, v0
	v_mov_b32_e32 v21, v0
	v_mov_b32_e32 v22, v0
	v_mov_b32_e32 v23, v0
	v_mov_b32_e32 v24, v0
	v_mov_b32_e32 v25, v0
	v_mov_b32_e32 v26, v0
	v_mov_b32_e32 v27, v0
	v_mov_b32_e32 v28, v0
	v_mov_b32_e32 v29, v0
	v_mov_b32_e32 v30, v0
	v_mov_b32_e32 v31, v0
	v_mov_b32_e32 v32, v0
	v_mov_b32_e32 v33, v0
	v_mov_b32_e32 v34, v0
	v_mov_b32_e32 v35, v0
	v_mov_b32_e32 v36, v0
	v_mov_b32_e32 v37, v0
	v_mov_b32_e32 v38, v0
	v_mov_b32_e32 v39, v0
	v_mov_b32_e32 v40, v0
	v_mov_b32_e32 v41, v0
	v_mov_b32_e32 v42, v0
	v_mov_b32_e32 v43, v0
	v_mov_b32_e32 v44, v0
	v_mov_b32_e32 v45, v0
	v_mov_b32_e32 v46, v0
	v_mov_b32_e32 v47, v0
	v_mov_b32_e32 v48, v0
	v_mov_b32_e32 v49, v0
	v_mov_b32_e32 v50, v0
	v_mov_b32_e32 v51, v0
	v_mov_b32_e32 v52, v0
	v_mov_b32_e32 v53, v0
	v_mov_b32_e32 v54, v0
	v_mov_b32_e32 v55, v0
	v_mov_b32_e32 v56, v0
	v_mov_b32_e32 v57, v0
	v_mov_b32_e32 v58, v0
	v_mov_b32_e32 v59, v0
	v_mov_b32_e32 v60, v0
	v_mov_b32_e32 v61, v0
	v_mov_b32_e32 v62, v0
	v_mov_b32_e32 v63, v0
	v_mov_b32_e32 v64, v0
	v_mov_b32_e32 v65, v0
	v_mov_b32_e32 v66, v0
	v_mov_b32_e32 v67, v0
	v_mov_b32_e32 v68, v0
	v_mov_b32_e32 v69, v0
	v_mov_b32_e32 v70, v0
	v_mov_b32_e32 v71, v0
	v_mov_b32_e32 v72, v0
	v_mov_b32_e32 v73, v0
	v_mov_b32_e32 v74, v0
	v_mov_b32_e32 v75, v0
	v_mov_b32_e32 v76, v0
	v_mov_b32_e32 v77, v0
	v_mov_b32_e32 v78, v0
	v_mov_b32_e32 v79, v0
	v_mov_b32_e32 v80, v0
	v_mov_b32_e32 v81, v0
	v_mov_b32_e32 v82, v0
	v_mov_b32_e32 v83, v0
	v_mov_b32_e32 v84, v0
	v_mov_b32_e32 v85, v0
	v_mov_b32_e32 v86, v0
	v_mov_b32_e32 v87, v0
	v_mov_b32_e32 v88, v0
	v_mov_b32_e32 v89, v0
	v_mov_b32_e32 v90, v0
	v_mov_b32_e32 v91, v0
	v_mov_b32_e32 v92, v0
	v_mov_b32_e32 v93, v0
	v_mov_b32_e32 v94, v0
	v_mov_b32_e32 v95, v0
	v_mov_b32_e32 v96, v0
	v_mov_b32_e32 v97, v0
	v_mov_b32_e32 v98, v0
	v_mov_b32_e32 v99, v0
	v_mov_b32_e32 v100, v0
	v_mov_b32_e32 v101, v0
	v_mov_b32_e32 v102, v0
	v_mov_b32_e32 v103, v0
	v_mov_b32_e32 v104, v0
	v_mov_b32_e32 v105, v0
	v_mov_b32_e32 v106, v0
	v_mov_b32_e32 v107, v0
	v_mov_b32_e32 v108, v0
	v_mov_b32_e32 v109, v0
	v_mov_b32_e32 v110, v0
	v_mov_b32_e32 v111, v0
	v_mov_b32_e32 v112, v0
	v_mov_b32_e32 v113, v0
	v_mov_b32_e32 v114, v0
	v_mov_b32_e32 v115, v0
	v_mov_b32_e32 v116, v0
	v_mov_b32_e32 v117, v0
	v_mov_b32_e32 v118, v0
	v_mov_b32_e32 v119, v0
	v_mov_b32_e32 v120, v0
	v_mov_b32_e32 v121, v0
	v_mov_b32_e32 v122, v0
	v_mov_b32_e32 v123, v0
	v_mov_b32_e32 v124, v0
	v_mov_b32_e32 v125, v0
	v_mov_b32_e32 v126, v0
	v_mov_b32_e32 v127, v0
	s_barrier
	s_branch .LBB0_292

; #define PG8_STAGE(bufoff, gbase, voff) do { _Pragma("unroll") for (int _i = 0; _i < 2; ++_i) glds16_s((gbase), (voff)[_i], ldsb + (unsigned)((bufoff) + _i * 8192)); } while (0)
; #define PG8_WAIT_V(n) asm volatile("s_waitcnt vmcnt(" #n ")" ::: "memory")
; #define PG8_BAR __builtin_amdgcn_s_barrier()
; template <class Prob, class Epi, bool I8 = false, bool ALIGN_EPI = true, bool SP2 = true>
; __device__ __forceinline__ void gemm_phase(LAS unsigned char* lds, int wave, const Prob& P, const Epi& E) {
;     ...
;     const char* cA = P.a_tile(cur); const char* cB = P.b_tile(cur);
;     if constexpr (SP2) {
;         PG8_STAGE(PG8_SB(0, 0), cB, voffB); PG8_STAGE(PG8_SB(0, 1), cB + hstepB, voffB); PG8_STAGE(PG8_SA(0, 0), cA, voffA); PG8_STAGE(PG8_SA(0, 1), cA + hstepA, voffA);
;         if (wr == 1) PG8_BAR;
;         PG8_WAIT_V(2); PG8_BAR;
;         PG8_STAGE(PG8_SB(1, 0), cB + kstep, voffB); PG8_STAGE(PG8_SA(1, 0), cA + kstep, voffA); PG8_STAGE(PG8_SB(1, 1), cB + hstepB + kstep, voffB);
;         PG8_WAIT_V(6); PG8_BAR;
.LBB0_458:
	v_and_b32_e32 v1, 48, v0
	v_lshlrev_b32_e32 v2, 6, v0
	s_movk_i32 s5, 0x3c0
	v_lshlrev_b32_e32 v0, 2, v0
	s_lshl_b32 s64, s1, 6
	s_lshl_b32 s1, s1, 13
	v_and_or_b32 v1, v2, s5, v1
	v_and_b32_e32 v0, 32, v0
	v_bitop3_b32 v2, v1, s1, v0 bitop3:0xde
	s_lshl_b32 s1, s4, 5
	s_and_b32 s68, s1, 0x60
	s_lshl_b32 s1, s68, 7
	s_add_u32 s4, s40, 0x80
	v_bitop3_b32 v0, s1, v1, v0 bitop3:0xf6
	s_addc_u32 s5, s41, 0
	s_add_i32 s69, s50, 0x18000
	s_mov_b32 s1, m0
	s_mov_b32 m0, s69
	s_nop 0
	global_load_lds_dwordx4 v143, s[4:5]
	s_mov_b32 m0, s1
	s_add_i32 s72, s50, 0x1a000
	s_mov_b32 s1, m0
	s_mov_b32 m0, s72
	s_nop 0
	global_load_lds_dwordx4 v145, s[4:5]
	s_mov_b32 m0, s1
	s_add_u32 s4, s44, 0x80
	s_addc_u32 s5, s45, 0
	s_add_i32 s73, s50, 0x8000
	s_mov_b32 s1, m0
	s_mov_b32 m0, s73
	s_nop 0
	global_load_lds_dwordx4 v142, s[4:5]
	s_mov_b32 m0, s1
	s_add_i32 s74, s50, 0xa000
	s_mov_b32 s1, m0
	s_mov_b32 m0, s74
	s_nop 0
	global_load_lds_dwordx4 v144, s[4:5]
	s_mov_b32 m0, s1
	s_add_u32 s4, s40, 0x80080
	s_addc_u32 s5, s41, 0
	s_add_i32 s75, s50, 0x1c000
	s_mov_b32 s1, m0
	s_mov_b32 m0, s75
	s_nop 0
	global_load_lds_dwordx4 v143, s[4:5]
	s_mov_b32 m0, s1
	s_add_i32 s76, s50, 0x1e000
	s_mov_b32 s1, m0
	s_mov_b32 m0, s76
	s_nop 0
	global_load_lds_dwordx4 v145, s[4:5]
	s_mov_b32 m0, s1
	s_waitcnt vmcnt(8)
	s_barrier
	s_waitcnt vmcnt(6)
	s_add_i32 s77, s50, 0xc000
	s_cmpk_lt_u32 s0, 0x100
	v_readlane_b32 s0, v252, 36
	s_cselect_b64 s[16:17], -1, 0
	s_add_i32 s79, s50, 0xe000
	s_mov_b32 s80, 0
	v_add_u32_e32 v146, 0, v0
	v_add_u32_e32 v147, 0, v2
	v_readlane_b32 s82, v252, 31
	s_mov_b32 s81, s0
	s_barrier
	v_readlane_b32 s1, v252, 37
	s_branch .LBB0_461

; #define PG8_STAGE(bufoff, gbase, voff) do { _Pragma("unroll") for (int _i = 0; _i < 2; ++_i) glds16_s((gbase), (voff)[_i], ldsb + (unsigned)((bufoff) + _i * 8192)); } while (0)
; #define PG8_WAIT_V(n) asm volatile("s_waitcnt vmcnt(" #n ")" ::: "memory")
; #define PG8_BAR __builtin_amdgcn_s_barrier()
; template <class Prob, class Epi, bool I8 = false, bool ALIGN_EPI = true, bool SP2 = true>
; __device__ __forceinline__ void gemm_phase(LAS unsigned char* lds, int wave, const Prob& P, const Epi& E) {
;     ...
;     const char* cA = P.a_tile(cur); const char* cB = P.b_tile(cur);
;     if constexpr (SP2) {
;         PG8_STAGE(PG8_SB(0, 0), cB, voffB); PG8_STAGE(PG8_SB(0, 1), cB + hstepB, voffB); PG8_STAGE(PG8_SA(0, 0), cA, voffA); PG8_STAGE(PG8_SA(0, 1), cA + hstepA, voffA);
;         if (wr == 1) PG8_BAR;
;         PG8_WAIT_V(2); PG8_BAR;
;         PG8_STAGE(PG8_SB(1, 0), cB + kstep, voffB); PG8_STAGE(PG8_SA(1, 0), cA + kstep, voffA); PG8_STAGE(PG8_SB(1, 1), cB + hstepB + kstep, voffB);
;         PG8_WAIT_V(6); PG8_BAR;
.LBB0_530:
	s_add_u32 s22, s30, 0x2d200000
	v_and_b32_e32 v1, 48, v0
	v_lshlrev_b32_e32 v2, 6, v0
	s_movk_i32 s5, 0x3c0
	v_lshlrev_b32_e32 v0, 2, v0
	s_addc_u32 s23, s31, 0
	s_and_b32 s4, s1, 3
	s_lshl_b32 s83, s2, 6
	s_lshl_b32 s2, s2, 13
	v_and_or_b32 v1, v2, s5, v1
	v_and_b32_e32 v0, 32, v0
	v_bitop3_b32 v2, v1, s2, v0 bitop3:0xde
	s_lshl_b32 s84, s4, 5
	s_lshl_b32 s2, s4, 12
	s_add_u32 s4, s38, 0x80
	v_bitop3_b32 v0, v1, s2, v0 bitop3:0xde
	s_addc_u32 s5, s39, 0
	s_add_i32 s85, s63, 0x18000
	s_mov_b32 s2, m0
	s_mov_b32 m0, s85
	s_nop 0
	global_load_lds_dwordx4 v133, s[4:5]
	s_mov_b32 m0, s2
	s_add_i32 s86, s63, 0x1a000
	s_mov_b32 s2, m0
	s_mov_b32 m0, s86
	s_nop 0
	global_load_lds_dwordx4 v135, s[4:5]
	s_mov_b32 m0, s2
	s_add_u32 s4, s40, 0x80
	s_addc_u32 s5, s41, 0
	s_add_i32 s87, s63, 0x8000
	s_mov_b32 s2, m0
	s_mov_b32 m0, s87
	s_nop 0
	global_load_lds_dwordx4 v132, s[4:5]
	s_mov_b32 m0, s2
	s_add_i32 s88, s63, 0xa000
	s_mov_b32 s2, m0
	s_mov_b32 m0, s88
	s_nop 0
	global_load_lds_dwordx4 v134, s[4:5]
	s_mov_b32 m0, s2
	s_add_u32 s4, s38, 0x80080
	s_addc_u32 s5, s39, 0
	s_add_i32 s89, s63, 0x1c000
	s_add_i32 s90, s63, 0x1e000
	s_add_i32 s91, s63, 0xc000
	s_mov_b32 s2, m0
	s_mov_b32 m0, s89
	s_nop 0
	global_load_lds_dwordx4 v133, s[4:5]
	s_mov_b32 m0, s2
	s_cmpk_lt_u32 s0, 0x100
	s_mov_b32 s2, m0
	s_mov_b32 m0, s90
	s_nop 0
	global_load_lds_dwordx4 v135, s[4:5]
	s_mov_b32 m0, s2
	s_cselect_b64 s[28:29], -1, 0
	s_lshl_b32 s0, s1, 6
	s_waitcnt vmcnt(8)
	s_barrier
	s_waitcnt vmcnt(6)
	s_and_b32 s0, s0, 0x80
	s_or_b32 s93, s0, 0xfffff400
	v_readlane_b32 s0, v252, 50
	s_and_b32 s92, s84, 32
	s_add_i32 s94, s63, 0xe000
	s_mov_b32 s95, 0
	v_add_u32_e32 v136, 0, v0
	v_add_u32_e32 v137, 0, v2
	v_readlane_b32 s2, v252, 34
	s_mov_b32 s56, s0
	s_barrier
	v_readlane_b32 s1, v252, 51
	s_branch .LBB0_533

; #define PG8_STAGE(bufoff, gbase, voff) do { _Pragma("unroll") for (int _i = 0; _i < 2; ++_i) glds16_s((gbase), (voff)[_i], ldsb + (unsigned)((bufoff) + _i * 8192)); } while (0)
; #define PG8_WAIT_V(n) asm volatile("s_waitcnt vmcnt(" #n ")" ::: "memory")
; #define PG8_BAR __builtin_amdgcn_s_barrier()
; template <class Prob, class Epi, bool I8 = false, bool ALIGN_EPI = true, bool SP2 = true>
; __device__ __forceinline__ void gemm_phase(LAS unsigned char* lds, int wave, const Prob& P, const Epi& E) {
;     ...
;     const char* cA = P.a_tile(cur); const char* cB = P.b_tile(cur);
;     if constexpr (SP2) {
;         PG8_STAGE(PG8_SB(0, 0), cB, voffB); PG8_STAGE(PG8_SB(0, 1), cB + hstepB, voffB); PG8_STAGE(PG8_SA(0, 0), cA, voffA); PG8_STAGE(PG8_SA(0, 1), cA + hstepA, voffA);
;         if (wr == 1) PG8_BAR;
;         PG8_WAIT_V(2); PG8_BAR;
;         PG8_STAGE(PG8_SB(1, 0), cB + kstep, voffB); PG8_STAGE(PG8_SA(1, 0), cA + kstep, voffA); PG8_STAGE(PG8_SB(1, 1), cB + hstepB + kstep, voffB);
;         PG8_WAIT_V(6); PG8_BAR;
.LBB0_610:
	v_and_b32_e32 v1, 48, v0
	v_lshlrev_b32_e32 v2, 6, v0
	s_movk_i32 s6, 0x3c0
	v_lshlrev_b32_e32 v0, 2, v0
	s_and_b32 s5, s0, 3
	s_lshl_b32 s88, s4, 6
	s_lshl_b32 s4, s4, 13
	v_and_or_b32 v1, v2, s6, v1
	v_and_b32_e32 v0, 32, v0
	v_bitop3_b32 v2, v1, s4, v0 bitop3:0xde
	s_lshl_b32 s89, s5, 5
	s_lshl_b32 s4, s5, 12
	s_add_u32 s16, s30, 0x240000
	v_bitop3_b32 v0, v1, s4, v0 bitop3:0xde
	s_addc_u32 s17, s31, 0
	v_readlane_b32 s4, v253, 55
	v_readlane_b32 s5, v253, 56
	s_add_u32 s4, s30, s4
	s_addc_u32 s5, s31, s5
	s_add_u32 s22, s4, 0x22c000
	s_addc_u32 s23, s5, 0
	s_add_u32 s4, s44, 0x80
	s_addc_u32 s5, s45, 0
	s_add_i32 s90, s2, 0x18000
	s_mov_b32 s6, m0
	s_mov_b32 m0, s90
	s_nop 0
	global_load_lds_dwordx4 v149, s[4:5]
	s_mov_b32 m0, s6
	s_add_i32 s91, s2, 0x1a000
	s_mov_b32 s6, m0
	s_mov_b32 m0, s91
	s_nop 0
	global_load_lds_dwordx4 v151, s[4:5]
	s_mov_b32 m0, s6
	s_add_u32 s4, s56, 0x80
	s_addc_u32 s5, s57, 0
	s_add_i32 s92, s2, 0x8000
	s_mov_b32 s6, m0
	s_mov_b32 m0, s92
	s_nop 0
	global_load_lds_dwordx4 v148, s[4:5]
	s_mov_b32 m0, s6
	s_add_i32 s93, s2, 0xa000
	s_mov_b32 s6, m0
	s_mov_b32 m0, s93
	s_nop 0
	global_load_lds_dwordx4 v150, s[4:5]
	s_mov_b32 m0, s6
	s_add_u32 s4, s44, 0x40080
	s_addc_u32 s5, s45, 0
	s_add_i32 s94, s2, 0x1c000
	s_mov_b32 s6, m0
	s_mov_b32 m0, s94
	s_nop 0
	global_load_lds_dwordx4 v149, s[4:5]
	s_mov_b32 m0, s6
	s_add_i32 s95, s2, 0x1e000
	s_mov_b32 s6, m0
	s_mov_b32 m0, s95
	s_nop 0
	global_load_lds_dwordx4 v151, s[4:5]
	s_mov_b32 m0, s6
	s_add_i32 s96, s2, 0xc000
	s_waitcnt vmcnt(8)
	s_barrier
	s_waitcnt vmcnt(6)
	s_cmpk_lt_u32 s1, 0x100
	s_cselect_b64 s[28:29], -1, 0
	s_lshl_b32 s0, s0, 6
	s_and_b32 s97, s89, 32
	s_and_b32 s74, s0, 0x80
	s_add_i32 s75, s2, 0xe000
	s_mov_b32 s72, 0
	v_add_u32_e32 v152, 0, v0
	v_add_u32_e32 v153, 0, v2
	s_barrier
	s_branch .LBB0_613

; #define PG8_STAGE(bufoff, gbase, voff) do { _Pragma("unroll") for (int _i = 0; _i < 2; ++_i) glds16_s((gbase), (voff)[_i], ldsb + (unsigned)((bufoff) + _i * 8192)); } while (0)
; #define PG8_WAIT_V(n) asm volatile("s_waitcnt vmcnt(" #n ")" ::: "memory")
; #define PG8_BAR __builtin_amdgcn_s_barrier()
; template <class Prob, class Epi, bool I8 = false, bool ALIGN_EPI = true, bool SP2 = true>
; __device__ __forceinline__ void gemm_phase(LAS unsigned char* lds, int wave, const Prob& P, const Epi& E) {
;     ...
;     const char* cA = P.a_tile(cur); const char* cB = P.b_tile(cur);
;     if constexpr (SP2) {
;         PG8_STAGE(PG8_SB(0, 0), cB, voffB); PG8_STAGE(PG8_SB(0, 1), cB + hstepB, voffB); PG8_STAGE(PG8_SA(0, 0), cA, voffA); PG8_STAGE(PG8_SA(0, 1), cA + hstepA, voffA);
;         if (wr == 1) PG8_BAR;
;         PG8_WAIT_V(2); PG8_BAR;
;         PG8_STAGE(PG8_SB(1, 0), cB + kstep, voffB); PG8_STAGE(PG8_SA(1, 0), cA + kstep, voffA); PG8_STAGE(PG8_SB(1, 1), cB + hstepB + kstep, voffB);
;         PG8_WAIT_V(6); PG8_BAR;
.LBB0_857:
	v_and_b32_e32 v1, 48, v0
	v_lshlrev_b32_e32 v2, 6, v0
	s_movk_i32 s5, 0x3c0
	v_lshlrev_b32_e32 v0, 2, v0
	s_lshl_b32 s62, s1, 6
	s_lshl_b32 s1, s1, 13
	v_and_or_b32 v1, v2, s5, v1
	v_and_b32_e32 v0, 32, v0
	v_bitop3_b32 v2, v1, s1, v0 bitop3:0xde
	s_lshl_b32 s1, s4, 5
	s_and_b32 s63, s1, 0x60
	s_lshl_b32 s1, s63, 7
	s_add_u32 s4, s40, 0x80
	v_bitop3_b32 v0, s1, v1, v0 bitop3:0xf6
	s_addc_u32 s5, s41, 0
	s_add_i32 s64, s48, 0x18000
	s_mov_b32 s1, m0
	s_mov_b32 m0, s64
	s_nop 0
	global_load_lds_dwordx4 v143, s[4:5]
	s_mov_b32 m0, s1
	s_add_i32 s68, s48, 0x1a000
	s_mov_b32 s1, m0
	s_mov_b32 m0, s68
	s_nop 0
	global_load_lds_dwordx4 v145, s[4:5]
	s_mov_b32 m0, s1
	s_add_u32 s4, s42, 0x80
	s_addc_u32 s5, s43, 0
	s_add_i32 s69, s48, 0x8000
	s_mov_b32 s1, m0
	s_mov_b32 m0, s69
	s_nop 0
	global_load_lds_dwordx4 v142, s[4:5]
	s_mov_b32 m0, s1
	s_add_i32 s72, s48, 0xa000
	s_mov_b32 s1, m0
	s_mov_b32 m0, s72
	s_nop 0
	global_load_lds_dwordx4 v144, s[4:5]
	s_mov_b32 m0, s1
	s_add_u32 s4, s40, 0x80080
	s_addc_u32 s5, s41, 0
	s_add_i32 s73, s48, 0x1c000
	s_mov_b32 s1, m0
	s_mov_b32 m0, s73
	s_nop 0
	global_load_lds_dwordx4 v143, s[4:5]
	s_mov_b32 m0, s1
	s_add_i32 s74, s48, 0x1e000
	s_mov_b32 s1, m0
	s_mov_b32 m0, s74
	s_nop 0
	global_load_lds_dwordx4 v145, s[4:5]
	s_mov_b32 m0, s1
	s_waitcnt vmcnt(8)
	s_barrier
	s_waitcnt vmcnt(6)
	s_add_i32 s75, s48, 0xc000
	s_cmpk_lt_u32 s0, 0x100
	v_readlane_b32 s0, v252, 36
	s_cselect_b64 s[16:17], -1, 0
	s_add_i32 s79, s48, 0xe000
	s_mov_b32 s80, 0
	v_add_u32_e32 v146, 0, v0
	v_add_u32_e32 v147, 0, v2
	v_readlane_b32 s82, v252, 31
	s_mov_b32 s81, s0
	s_barrier
	v_readlane_b32 s1, v252, 37
	s_branch .LBB0_860

; #define PG8_STAGE(bufoff, gbase, voff) do { _Pragma("unroll") for (int _i = 0; _i < 2; ++_i) glds16_s((gbase), (voff)[_i], ldsb + (unsigned)((bufoff) + _i * 8192)); } while (0)
; #define PG8_WAIT_V(n) asm volatile("s_waitcnt vmcnt(" #n ")" ::: "memory")
; #define PG8_BAR __builtin_amdgcn_s_barrier()
; template <class Prob, class Epi, bool I8 = false, bool ALIGN_EPI = true, bool SP2 = true>
; __device__ __forceinline__ void gemm_phase(LAS unsigned char* lds, int wave, const Prob& P, const Epi& E) {
;     ...
;     const char* cA = P.a_tile(cur); const char* cB = P.b_tile(cur);
;     if constexpr (SP2) {
;         PG8_STAGE(PG8_SB(0, 0), cB, voffB); PG8_STAGE(PG8_SB(0, 1), cB + hstepB, voffB); PG8_STAGE(PG8_SA(0, 0), cA, voffA); PG8_STAGE(PG8_SA(0, 1), cA + hstepA, voffA);
;         if (wr == 1) PG8_BAR;
;         PG8_WAIT_V(2); PG8_BAR;
;         PG8_STAGE(PG8_SB(1, 0), cB + kstep, voffB); PG8_STAGE(PG8_SA(1, 0), cA + kstep, voffA); PG8_STAGE(PG8_SB(1, 1), cB + hstepB + kstep, voffB);
;         PG8_WAIT_V(6); PG8_BAR;
.LBB0_989:
	s_add_u32 s22, s44, 0x80
	s_addc_u32 s23, s45, 0
	s_add_u32 s4, s4, 0xfffff880
	s_addc_u32 s5, s5, -1
	s_add_u32 s28, s44, 0x40080
	v_and_b32_e32 v1, 48, v0
	v_lshlrev_b32_e32 v2, 6, v0
	s_movk_i32 s6, 0x3c0
	v_lshlrev_b32_e32 v0, 2, v0
	s_addc_u32 s29, s45, 0
	s_lshl_b32 s74, s1, 6
	s_lshl_b32 s1, s1, 13
	v_and_or_b32 v1, v2, s6, v1
	v_and_b32_e32 v0, 32, v0
	v_bitop3_b32 v2, v1, s1, v0 bitop3:0xde
	s_lshl_b32 s1, s16, 5
	s_and_b32 s75, s1, 0x60
	s_lshl_b32 s1, s75, 7
	v_bitop3_b32 v0, s1, v1, v0 bitop3:0xf6
	s_add_i32 s76, s2, 0x18000
	s_mov_b32 s1, m0
	s_mov_b32 m0, s76
	s_nop 0
	global_load_lds_dwordx4 v130, s[22:23]
	s_mov_b32 m0, s1
	s_add_i32 s77, s2, 0x1a000
	s_mov_b32 s1, m0
	s_mov_b32 m0, s77
	s_nop 0
	global_load_lds_dwordx4 v132, s[22:23]
	s_mov_b32 m0, s1
	s_add_i32 s80, s2, 0x8000
	s_mov_b32 s1, m0
	s_mov_b32 m0, s80
	s_nop 0
	global_load_lds_dwordx4 v129, s[4:5]
	s_mov_b32 m0, s1
	s_add_i32 s81, s2, 0xa000
	s_mov_b32 s1, m0
	s_mov_b32 m0, s81
	s_nop 0
	global_load_lds_dwordx4 v131, s[4:5]
	s_mov_b32 m0, s1
	s_add_i32 s82, s2, 0x1c000
	s_mov_b32 s1, m0
	s_mov_b32 m0, s82
	s_nop 0
	global_load_lds_dwordx4 v130, s[28:29]
	s_mov_b32 m0, s1
	s_add_i32 s83, s2, 0x1e000
	s_mov_b32 s1, m0
	s_mov_b32 m0, s83
	s_nop 0
	global_load_lds_dwordx4 v132, s[28:29]
	s_mov_b32 m0, s1
	s_add_i32 s84, s2, 0xc000
	s_cmpk_lt_u32 s0, 0x100
	v_readlane_b32 s0, v252, 19
	s_waitcnt vmcnt(8)
	s_barrier
	s_waitcnt vmcnt(6)
	v_readlane_b32 s1, v252, 20
	s_mov_b32 s87, s0
	v_readlane_b32 s0, v252, 15
	s_cselect_b64 s[16:17], -1, 0
	s_add_i32 s85, s2, 0xe000
	s_mov_b32 s86, 0
	v_add_u32_e32 v133, 0, v0
	v_add_u32_e32 v134, 0, v2
	s_mov_b32 s88, s0
	s_barrier
	v_readlane_b32 s1, v252, 16
	s_branch .LBB0_992

; #define PG8_STAGE(bufoff, gbase, voff) do { _Pragma("unroll") for (int _i = 0; _i < 2; ++_i) glds16_s((gbase), (voff)[_i], ldsb + (unsigned)((bufoff) + _i * 8192)); } while (0)
; #define PG8_WAIT_V(n) asm volatile("s_waitcnt vmcnt(" #n ")" ::: "memory")
; #define PG8_BAR __builtin_amdgcn_s_barrier()
; template <class Prob, class Epi, bool I8 = false, bool ALIGN_EPI = true, bool SP2 = true>
; __device__ __forceinline__ void gemm_phase(LAS unsigned char* lds, int wave, const Prob& P, const Epi& E) {
;     ...
;     const char* cA = P.a_tile(cur); const char* cB = P.b_tile(cur);
;     if constexpr (SP2) {
;         PG8_STAGE(PG8_SB(0, 0), cB, voffB); PG8_STAGE(PG8_SB(0, 1), cB + hstepB, voffB); PG8_STAGE(PG8_SA(0, 0), cA, voffA); PG8_STAGE(PG8_SA(0, 1), cA + hstepA, voffA);
;         if (wr == 1) PG8_BAR;
;         PG8_WAIT_V(2); PG8_BAR;
;         PG8_STAGE(PG8_SB(1, 0), cB + kstep, voffB); PG8_STAGE(PG8_SA(1, 0), cA + kstep, voffA); PG8_STAGE(PG8_SB(1, 1), cB + hstepB + kstep, voffB);
;         PG8_WAIT_V(6); PG8_BAR;
.LBB0_1059:
	v_readlane_b32 s6, v255, 1
	v_readlane_b32 s84, v251, 4
	s_mul_i32 s2, s6, 0x8400
	v_readlane_b32 s86, v251, 6
	v_readlane_b32 s87, v251, 7
	s_lshl_b64 s[4:5], s[2:3], 2
	s_mov_b64 s[46:47], s[86:87]
	s_add_u32 s22, s46, s4
	v_and_b32_e32 v1, 15, v0
	v_and_b32_e32 v2, 48, v0
	v_lshlrev_b32_e32 v0, 2, v0
	s_addc_u32 s23, s47, s5
	v_lshl_or_b32 v1, v1, 6, v2
	s_lshl_b32 s2, s64, 13
	v_and_b32_e32 v0, 32, v0
	s_lshl_b32 s1, s1, 5
	v_bitop3_b32 v2, v1, s2, v0 bitop3:0xde
	s_and_b32 s84, s1, 0x60
	s_mul_i32 s2, s6, 0x2c00
	s_lshl_b32 s1, s84, 7
	s_lshl_b64 s[4:5], s[2:3], 2
	v_bitop3_b32 v0, s1, v1, v0 bitop3:0xf6
	s_add_u32 s1, s30, s4
	s_addc_u32 s2, s31, s5
	s_add_u32 s28, s1, 0x200000
	s_addc_u32 s29, s2, 0
	v_readlane_b32 s85, v251, 5
	s_add_u32 s4, s44, 0x80
	s_addc_u32 s5, s45, 0
	s_add_i32 s2, s72, 0x18000
	s_mov_b32 s1, m0
	s_mov_b32 m0, s2
	s_nop 0
	global_load_lds_dwordx4 v217, s[4:5]
	s_mov_b32 m0, s1
	s_add_i32 s85, s72, 0x1a000
	s_mov_b32 s1, m0
	s_mov_b32 m0, s85
	s_nop 0
	global_load_lds_dwordx4 v248, s[4:5]
	s_mov_b32 m0, s1
	s_add_u32 s4, s60, 0x80
	s_addc_u32 s5, s61, 0
	s_add_i32 s86, s72, 0x8000
	s_mov_b32 s1, m0
	s_mov_b32 m0, s86
	s_nop 0
	global_load_lds_dwordx4 v250, s[4:5]
	s_mov_b32 m0, s1
	s_add_i32 s87, s72, 0xa000
	v_readlane_b32 s88, v251, 8
	s_mov_b32 s1, m0
	s_mov_b32 m0, s87
	s_nop 0
	global_load_lds_dwordx4 v247, s[4:5]
	s_mov_b32 m0, s1
	s_add_u32 s4, s44, 0x40080
	v_readlane_b32 s89, v251, 9
	s_addc_u32 s5, s45, 0
	s_add_i32 s88, s72, 0x1c000
	s_mov_b32 s1, m0
	s_mov_b32 m0, s88
	s_nop 0
	global_load_lds_dwordx4 v217, s[4:5]
	s_mov_b32 m0, s1
	v_readlane_b32 s90, v251, 10
	s_add_i32 s89, s72, 0x1e000
	s_mov_b32 s1, m0
	s_mov_b32 m0, s89
	s_nop 0
	global_load_lds_dwordx4 v248, s[4:5]
	s_mov_b32 m0, s1
	s_waitcnt vmcnt(8)
	s_barrier
	s_waitcnt vmcnt(6)
	s_add_i32 s90, s72, 0xc000
	v_readlane_b32 s91, v251, 11
	s_cmpk_lt_u32 s0, 0x100
	v_readlane_b32 s0, v252, 54
	s_cselect_b64 s[46:47], -1, 0
	s_lshl_b32 s91, s64, 7
	s_add_i32 s92, s72, 0xe000
	s_mov_b32 s93, 0
	v_add_u32_e32 v210, 0, v0
	v_add_u32_e32 v211, 0, v2
	v_readlane_b32 s94, v252, 35
	s_mov_b32 s95, s0
	s_barrier
	v_readlane_b32 s1, v252, 55
	s_branch .LBB0_1062

; #define PG8_STAGE(bufoff, gbase, voff) do { _Pragma("unroll") for (int _i = 0; _i < 2; ++_i) glds16_s((gbase), (voff)[_i], ldsb + (unsigned)((bufoff) + _i * 8192)); } while (0)
; #define PG8_WAIT_V(n) asm volatile("s_waitcnt vmcnt(" #n ")" ::: "memory")
; #define PG8_BAR __builtin_amdgcn_s_barrier()
; template <class Prob, class Epi, bool I8 = false, bool ALIGN_EPI = true, bool SP2 = true>
; __device__ __forceinline__ void gemm_phase(LAS unsigned char* lds, int wave, const Prob& P, const Epi& E) {
;     ...
;     const char* cA = P.a_tile(cur); const char* cB = P.b_tile(cur);
;     if constexpr (SP2) {
;         PG8_STAGE(PG8_SB(0, 0), cB, voffB); PG8_STAGE(PG8_SB(0, 1), cB + hstepB, voffB); PG8_STAGE(PG8_SA(0, 0), cA, voffA); PG8_STAGE(PG8_SA(0, 1), cA + hstepA, voffA);
;         if (wr == 1) PG8_BAR;
;         PG8_WAIT_V(2); PG8_BAR;
;         PG8_STAGE(PG8_SB(1, 0), cB + kstep, voffB); PG8_STAGE(PG8_SA(1, 0), cA + kstep, voffA); PG8_STAGE(PG8_SB(1, 1), cB + hstepB + kstep, voffB);
;         PG8_WAIT_V(6); PG8_BAR;
.LBB0_1206:
	v_readlane_b32 s80, v251, 16
	v_readlane_b32 s81, v251, 17
	v_readlane_b32 s82, v251, 18
	v_readlane_b32 s83, v251, 19
	v_readlane_b32 s92, v251, 28
	v_readlane_b32 s93, v251, 29
	v_readlane_b32 s94, v251, 30
	v_readlane_b32 s95, v251, 31
	s_mov_b64 s[80:81], s[92:93]
	s_mov_b64 s[82:83], s[94:95]
	v_readlane_b32 s6, v255, 2
	v_readlane_b32 s7, v255, 3
	s_add_u32 s22, s82, s6
	s_addc_u32 s23, s83, s7
	s_add_u32 s5, s30, s6
	s_addc_u32 s6, s31, s7
	s_add_u32 s26, s5, 0x232000
	v_and_b32_e32 v1, 48, v0
	v_lshlrev_b32_e32 v2, 6, v0
	s_movk_i32 s5, 0x3c0
	v_lshlrev_b32_e32 v0, 2, v0
	s_addc_u32 s27, s6, 0
	s_lshl_b32 s77, s1, 6
	s_lshl_b32 s1, s1, 13
	v_and_or_b32 v1, v2, s5, v1
	v_and_b32_e32 v0, 32, v0
	v_bitop3_b32 v2, v1, s1, v0 bitop3:0xde
	s_lshl_b32 s1, s4, 5
	s_and_b32 s79, s1, 0x60
	s_lshl_b32 s1, s79, 7
	s_add_u32 s28, s30, 0x280000
	s_addc_u32 s29, s31, 0
	s_add_u32 s46, s30, 0x1b00000
	s_addc_u32 s47, s31, 0
	s_add_u32 s4, s14, 0x80
	v_bitop3_b32 v0, s1, v1, v0 bitop3:0xf6
	s_addc_u32 s5, s15, 0
	s_add_i32 s80, s40, 0x18000
	s_mov_b32 s1, m0
	s_mov_b32 m0, s80
	s_nop 0
	global_load_lds_dwordx4 v161, s[4:5]
	s_mov_b32 m0, s1
	s_add_i32 s81, s40, 0x1a000
	s_mov_b32 s1, m0
	s_mov_b32 m0, s81
	s_nop 0
	global_load_lds_dwordx4 v163, s[4:5]
	s_mov_b32 m0, s1
	v_readlane_b32 s4, v252, 44
	s_add_i32 s82, s40, 0x8000
	v_readlane_b32 s5, v252, 45
	s_mov_b32 s1, m0
	s_mov_b32 m0, s82
	s_nop 0
	global_load_lds_dwordx4 v160, s[4:5]
	s_mov_b32 m0, s1
	s_add_i32 s83, s40, 0xa000
	v_readlane_b32 s84, v251, 20
	s_mov_b32 s1, m0
	s_mov_b32 m0, s83
	s_nop 0
	global_load_lds_dwordx4 v162, s[4:5]
	s_mov_b32 m0, s1
	s_add_u32 s4, s14, 0xb0080
	v_readlane_b32 s85, v251, 21
	s_addc_u32 s5, s15, 0
	s_add_i32 s84, s40, 0x1c000
	s_mov_b32 s1, m0
	s_mov_b32 m0, s84
	s_nop 0
	global_load_lds_dwordx4 v161, s[4:5]
	s_mov_b32 m0, s1
	v_readlane_b32 s86, v251, 22
	s_add_i32 s85, s40, 0x1e000
	s_mov_b32 s1, m0
	s_mov_b32 m0, s85
	s_nop 0
	global_load_lds_dwordx4 v163, s[4:5]
	s_mov_b32 m0, s1
	s_waitcnt vmcnt(8)
	s_barrier
	s_waitcnt vmcnt(6)
	s_add_i32 s86, s40, 0xc000
	v_readlane_b32 s87, v251, 23
	v_readlane_b32 s88, v251, 24
	s_cmpk_lt_u32 s0, 0x100
	v_readlane_b32 s0, v252, 36
	v_readlane_b32 s44, v252, 42
	v_readlane_b32 s89, v251, 25
	v_readlane_b32 s90, v251, 26
	s_cselect_b64 s[48:49], -1, 0
	s_add_i32 s87, s40, 0xe000
	s_mov_b32 s88, 0
	v_add_u32_e32 v179, 0, v0
	v_add_u32_e32 v185, 0, v2
	v_readlane_b32 s73, v252, 31
	s_mov_b32 s72, s0
	v_readlane_b32 s45, v252, 43
	v_readlane_b32 s91, v251, 27
	s_barrier
	v_readlane_b32 s1, v252, 37
	s_branch .LBB0_1209
